# P3 conv-unit gated epilogue: 16 gate loads up front; chain loop-top wait leaves the 8 row stores in flight; on top of P7+P3b+P4 epilogues
# speedup vs baseline: 1.0274x; 1.0002x over previous
; template <bool STORE> __device__ __forceinline__ void ret_chain(LAS unsigned char* lds, int b, int h, bf16* Qb, const bf16* Kb, const bf16* Vb, const bf16* Gb, const f32x2* tab, float* s_out) {
;     ...
;         const int Leff = ci == 0 ? NMETA : 128;
;         const int row_base = ci == 0 ? (R_META + b * NMETA) : (b * SEQ + (ci - 1) * 128);
; #pragma unroll
;         for (int it = 0; it < 4; ++it) {
;             const int item = tid + NTHREADS * it, j = item >> 4, c = item & 15;
;             const bool valid = j < Leff;
;             const float kd = valid ? __expf(lg * (float)(Leff - 1 - j)) : 0.f;
;             const u32x4 q = valid ? rq[it] : zero4u, k = valid ? rk[it] : zero4u, v = rv[it];
.LBB0_319:
	s_cmp_eq_u32 s45, 0
	s_cselect_b64 s[28:29], -1, 0
	s_and_b64 s[30:31], s[28:29], exec
	s_cselect_b32 s48, 16, 0x80
	v_not_b32_e32 v84, v215
	v_add_u32_e32 v84, s48, v84
	v_cvt_f32_i32_e32 v84, v84
	v_cmp_gt_i32_e32 vcc, s48, v215
	s_cmp_lt_u32 s45, 0x100
	s_cbranch_scc1 .Lchain_w0
	s_waitcnt vmcnt(8)
	s_branch .Lchain_w1

; __device__ __forceinline__ unsigned cvt_pk_bf16(float lo, float hi) { unsigned r; asm volatile("v_cvt_pk_bf16_f32 %0, %1, %2" : "=v"(r) : "v"(lo), "v"(hi)); return r; }
; #define LAS __attribute__((address_space(3)))
; #define CHAIN_BAR() do { asm volatile("s_waitcnt lgkmcnt(0)" ::: "memory"); __builtin_amdgcn_s_barrier(); asm volatile("" ::: "memory"); } while (0)
; template <bool STORE> __device__ __forceinline__ void ret_chain(LAS unsigned char* lds, int b, int h, bf16* Qb, const bf16* Kb, const bf16* Vb, const bf16* Gb, const f32x2* tab, float* s_out) {
;     ...
; #pragma unroll
;         for (int it = 0; it < 4; ++it) {
;             const int item = tid + NTHREADS * it, j = item >> 4, c = item & 15;
;             const bool valid = j < Leff;
;             const float kd = valid ? __expf(lg * (float)(Leff - 1 - j)) : 0.f;
;             const u32x4 q = valid ? rq[it] : zero4u, k = valid ? rk[it] : zero4u, v = rv[it];
;             u32x4 vs;
; #pragma unroll
;             for (int p = 0; p < 4; ++p) vs[p] = cvt_pk_bf16(bflo(v[p]) * kd, bfhi(v[p]) * kd);
;             const int boff = j * PTB + (8 * c) * 2;
;             *(LAS u32x4*)(lds + RG0 + boff) = q; *(LAS u32x4*)(lds + RG1 + boff) = k; *(LAS u32x4*)(lds + RG2 + boff) = vs;
;         }
;         CHAIN_BAR();
;         if (ci + 1 < 17) CHAIN_LOAD(ci + 1);
.Lchain_w1:
	v_lshlrev_b32_e32 v92, 16, v12
	v_and_b32_e32 v93, 0xffff0000, v12
	v_mul_f32_e32 v84, s33, v84
	v_mul_f32_e32 v84, 0x3fb8aa3b, v84
	v_exp_f32_e32 v84, v84
	v_and_b32_e32 v94, 0xffff0000, v13
	v_and_b32_e32 v96, 0xffff0000, v14
	v_and_b32_e32 v97, 0xffff0000, v15
	v_cndmask_b32_e32 v95, 0, v84, vcc
	v_mul_f32_e32 v92, v95, v92
	v_mul_f32_e32 v93, v95, v93
	v_cvt_pk_bf16_f32 v92, v92, v93
	v_lshlrev_b32_e32 v93, 16, v13
	v_mul_f32_e32 v93, v95, v93
	v_mul_f32_e32 v94, v95, v94
	v_cvt_pk_bf16_f32 v93, v93, v94
	v_lshlrev_b32_e32 v94, 16, v14
	v_mul_f32_e32 v94, v95, v94
	v_mul_f32_e32 v96, v95, v96
	v_cvt_pk_bf16_f32 v94, v94, v96
	v_lshlrev_b32_e32 v96, 16, v15
	v_mul_f32_e32 v96, v95, v96
	v_mul_f32_e32 v95, v95, v97
	v_cvt_pk_bf16_f32 v95, v96, v95
	v_not_b32_e32 v96, v216
	v_add_u32_e32 v96, s48, v96
	v_cvt_f32_i32_e32 v96, v96
	v_cndmask_b32_e32 v87, v3, v7, vcc
	v_cndmask_b32_e32 v86, v2, v6, vcc
	v_cndmask_b32_e32 v85, v1, v5, vcc
	v_cndmask_b32_e32 v84, v0, v4, vcc
	v_add_u32_e32 v97, 0, v196
	v_cndmask_b32_e32 v91, v3, v11, vcc
	v_cndmask_b32_e32 v90, v2, v10, vcc
	v_cndmask_b32_e32 v89, v1, v9, vcc
	v_cndmask_b32_e32 v88, v0, v8, vcc
	ds_write_b128 v97, v[84:87]
	ds_write_b128 v97, v[88:91] offset:34816
	v_mul_f32_e32 v84, s33, v96
	v_mul_f32_e32 v84, 0x3fb8aa3b, v84
	v_exp_f32_e32 v84, v84
	v_readlane_b32 s30, v254, 6
	v_cmp_gt_i32_e32 vcc, s48, v216
	v_and_b32_e32 v96, 0xffff0000, v26
	v_add_u32_e32 v85, s30, v196
	ds_write_b128 v85, v[92:95]
	v_cndmask_b32_e32 v95, 0, v84, vcc
	v_lshlrev_b32_e32 v92, 16, v24
	v_and_b32_e32 v93, 0xffff0000, v24
	v_mul_f32_e32 v92, v95, v92
	v_mul_f32_e32 v93, v95, v93
	v_cvt_pk_bf16_f32 v92, v92, v93
	v_lshlrev_b32_e32 v93, 16, v25
	v_and_b32_e32 v94, 0xffff0000, v25
	v_mul_f32_e32 v93, v95, v93
	v_mul_f32_e32 v94, v95, v94
	v_cvt_pk_bf16_f32 v93, v93, v94
	v_lshlrev_b32_e32 v94, 16, v26
	v_mul_f32_e32 v94, v95, v94
	v_mul_f32_e32 v96, v95, v96
	v_cvt_pk_bf16_f32 v94, v94, v96
	v_lshlrev_b32_e32 v96, 16, v27
	v_and_b32_e32 v97, 0xffff0000, v27
	v_mul_f32_e32 v96, v95, v96
	v_mul_f32_e32 v95, v95, v97
	v_cvt_pk_bf16_f32 v95, v96, v95
	v_not_b32_e32 v96, v217
	v_add_u32_e32 v96, s48, v96
	v_cvt_f32_i32_e32 v96, v96
	v_cndmask_b32_e32 v87, v3, v19, vcc
	v_cndmask_b32_e32 v86, v2, v18, vcc
	v_cndmask_b32_e32 v85, v1, v17, vcc
	v_cndmask_b32_e32 v84, v0, v16, vcc
	v_add_u32_e32 v97, 0, v198
	v_cndmask_b32_e32 v91, v3, v23, vcc
	v_cndmask_b32_e32 v90, v2, v22, vcc
	v_cndmask_b32_e32 v89, v1, v21, vcc
	v_cndmask_b32_e32 v88, v0, v20, vcc
	ds_write_b128 v97, v[84:87]
	ds_write_b128 v97, v[88:91] offset:34816
	v_mul_f32_e32 v84, s33, v96
	v_mul_f32_e32 v84, 0x3fb8aa3b, v84
	v_exp_f32_e32 v84, v84
	v_add_u32_e32 v85, s30, v198
	v_cmp_gt_i32_e32 vcc, s48, v217
	ds_write_b128 v85, v[92:95]
	v_lshlrev_b32_e32 v92, 16, v36
	v_cndmask_b32_e32 v95, 0, v84, vcc
	v_and_b32_e32 v93, 0xffff0000, v36
	v_mul_f32_e32 v92, v95, v92
	v_mul_f32_e32 v93, v95, v93
	v_cvt_pk_bf16_f32 v92, v92, v93
	v_lshlrev_b32_e32 v93, 16, v37
	v_and_b32_e32 v94, 0xffff0000, v37
	v_mul_f32_e32 v93, v95, v93
	v_mul_f32_e32 v94, v95, v94
	v_cvt_pk_bf16_f32 v93, v93, v94
	v_lshlrev_b32_e32 v94, 16, v38
	v_and_b32_e32 v96, 0xffff0000, v38
	v_mul_f32_e32 v94, v95, v94
	v_mul_f32_e32 v96, v95, v96
	v_cvt_pk_bf16_f32 v94, v94, v96
	v_lshlrev_b32_e32 v96, 16, v39
	v_and_b32_e32 v97, 0xffff0000, v39
	v_mul_f32_e32 v96, v95, v96
	v_mul_f32_e32 v95, v95, v97
	v_cvt_pk_bf16_f32 v95, v96, v95
	v_not_b32_e32 v96, v218
	v_add_u32_e32 v96, s48, v96
	v_cvt_f32_i32_e32 v96, v96
	v_cndmask_b32_e32 v87, v3, v31, vcc
	v_cndmask_b32_e32 v86, v2, v30, vcc
	v_cndmask_b32_e32 v85, v1, v29, vcc
	v_cndmask_b32_e32 v84, v0, v28, vcc
	v_add_u32_e32 v97, 0, v200
	v_cndmask_b32_e32 v91, v3, v35, vcc
	v_cndmask_b32_e32 v90, v2, v34, vcc
	v_cndmask_b32_e32 v89, v1, v33, vcc
	v_cndmask_b32_e32 v88, v0, v32, vcc
	ds_write_b128 v97, v[84:87]
	ds_write_b128 v97, v[88:91] offset:34816
	v_mul_f32_e32 v84, s33, v96
	v_mul_f32_e32 v84, 0x3fb8aa3b, v84
	v_exp_f32_e32 v84, v84
	v_add_u32_e32 v85, s30, v200
	v_cmp_gt_i32_e32 vcc, s48, v218
	ds_write_b128 v85, v[92:95]
	v_lshlrev_b32_e32 v92, 16, v48
	v_cndmask_b32_e32 v95, 0, v84, vcc
	v_and_b32_e32 v93, 0xffff0000, v48
	v_mul_f32_e32 v92, v95, v92
	v_mul_f32_e32 v93, v95, v93
	v_cvt_pk_bf16_f32 v92, v92, v93
	v_lshlrev_b32_e32 v93, 16, v49
	v_and_b32_e32 v94, 0xffff0000, v49
	v_mul_f32_e32 v93, v95, v93
	v_mul_f32_e32 v94, v95, v94
	v_cvt_pk_bf16_f32 v93, v93, v94
	v_lshlrev_b32_e32 v94, 16, v50
	v_and_b32_e32 v96, 0xffff0000, v50
	v_mul_f32_e32 v94, v95, v94
	v_mul_f32_e32 v96, v95, v96
	v_cvt_pk_bf16_f32 v94, v94, v96
	v_lshlrev_b32_e32 v96, 16, v51
	v_and_b32_e32 v97, 0xffff0000, v51
	v_mul_f32_e32 v96, v95, v96
	v_mul_f32_e32 v95, v95, v97
	v_cndmask_b32_e32 v87, v3, v43, vcc
	v_cndmask_b32_e32 v86, v2, v42, vcc
	v_cndmask_b32_e32 v85, v1, v41, vcc
	v_cndmask_b32_e32 v84, v0, v40, vcc
	v_cvt_pk_bf16_f32 v95, v96, v95
	v_add_u32_e32 v96, 0, v202
	v_cndmask_b32_e32 v91, v3, v47, vcc
	v_cndmask_b32_e32 v90, v2, v46, vcc
	v_cndmask_b32_e32 v89, v1, v45, vcc
	v_cndmask_b32_e32 v88, v0, v44, vcc
	ds_write_b128 v96, v[84:87]
	ds_write_b128 v96, v[88:91] offset:34816
	v_add_u32_e32 v84, s30, v202
	ds_write_b128 v84, v[92:95]
	s_waitcnt lgkmcnt(0)
	s_barrier
	s_cmpk_eq_i32 s45, 0x800
	s_cbranch_scc1 .LBB0_321
	v_add_u32_e32 v4, s45, v240
	v_add_u32_e32 v14, s45, v239
	v_add_u32_e32 v28, s45, v238
	v_add_u32_e32 v38, s45, v237
	v_ashrrev_i32_e32 v5, 31, v4
	v_ashrrev_i32_e32 v15, 31, v14
	v_ashrrev_i32_e32 v29, 31, v28
	v_ashrrev_i32_e32 v39, 31, v38
	v_lshlrev_b64 v[12:13], 11, v[4:5]
	v_lshlrev_b64 v[20:21], 11, v[14:15]
	v_lshlrev_b64 v[36:37], 11, v[28:29]
	v_lshlrev_b64 v[44:45], 11, v[38:39]
	v_or_b32_e32 v12, v12, v241
	v_or_b32_e32 v20, v20, v241
	v_or_b32_e32 v36, v36, v241
	v_or_b32_e32 v44, v44, v241
	v_lshl_add_u64 v[4:5], s[2:3], 0, v[12:13]
	v_lshl_add_u64 v[8:9], s[40:41], 0, v[12:13]
	v_lshl_add_u64 v[12:13], s[42:43], 0, v[12:13]
	v_lshl_add_u64 v[16:17], s[2:3], 0, v[20:21]
	v_lshl_add_u64 v[22:23], s[40:41], 0, v[20:21]
	v_lshl_add_u64 v[24:25], s[42:43], 0, v[20:21]
	v_lshl_add_u64 v[28:29], s[2:3], 0, v[36:37]
	v_lshl_add_u64 v[32:33], s[40:41], 0, v[36:37]
	v_lshl_add_u64 v[36:37], s[42:43], 0, v[36:37]
	v_lshl_add_u64 v[40:41], s[2:3], 0, v[44:45]
	v_lshl_add_u64 v[46:47], s[40:41], 0, v[44:45]
	v_lshl_add_u64 v[48:49], s[42:43], 0, v[44:45]
	global_load_dwordx4 v[4:7], v[4:5], off
	s_nop 0
	global_load_dwordx4 v[8:11], v[8:9], off
	s_nop 0
	global_load_dwordx4 v[12:15], v[12:13], off
	s_nop 0
	global_load_dwordx4 v[16:19], v[16:17], off
	s_nop 0
	global_load_dwordx4 v[20:23], v[22:23], off
	s_nop 0
	global_load_dwordx4 v[24:27], v[24:25], off
	s_nop 0
	global_load_dwordx4 v[28:31], v[28:29], off
	s_nop 0
	global_load_dwordx4 v[32:35], v[32:33], off
	s_nop 0
	global_load_dwordx4 v[36:39], v[36:37], off
	s_nop 0
	global_load_dwordx4 v[40:43], v[40:41], off
	s_nop 0
	global_load_dwordx4 v[44:47], v[46:47], off
	s_nop 0
	global_load_dwordx4 v[48:51], v[48:49], off

; #define PG8_STAGE(bufoff, gbase, voff) do { _Pragma("unroll") for (int _i = 0; _i < 2; ++_i) \
;         __builtin_amdgcn_global_load_lds((const unsigned*)((const char*)(gbase) + (voff)[_i]), (PG8_LAS unsigned*)(lds + (bufoff) + ldsw + _i * 8192), 16, 0, 0); } while (0)
; #define PG8_LDA(dst, b, h) do { _Pragma("unroll") for (int m = 0; m < 4; ++m) _Pragma("unroll") for (int k = 0; k < 2; ++k) dst[m][k] = *(const PG8_LAS bf16x8*)(lds + PG8_SA(b, h) + aoff + m * 2048 + k * 1024); } while (0)
; #define PG8_LDB(dst, b, h) do { _Pragma("unroll") for (int n = 0; n < 2; ++n) _Pragma("unroll") for (int k = 0; k < 2; ++k) dst[n][k] = *(const PG8_LAS bf16x8*)(lds + PG8_SB(b, h) + boff + n * 2048 + k * 1024); } while (0)
; #define PG8_MMA(ai, bj, At, Bt) do { __builtin_amdgcn_s_setprio(1); _Pragma("unroll") for (int m = 0; m < 4; ++m) _Pragma("unroll") for (int n = 0; n < 2; ++n) _Pragma("unroll") for (int k = 0; k < 2; ++k) \
;         acc[ai][bj][m][n] = __builtin_amdgcn_mfma_f32_16x16x32_bf16(Bt[n][k], At[m][k], acc[ai][bj][m][n], 0, 0, 0); __builtin_amdgcn_s_setprio(0); } while (0)
; #define PG8_WAIT_V(n) asm volatile("s_waitcnt vmcnt(" #n ")" ::: "memory")
; #define PG8_BAR __builtin_amdgcn_s_barrier()
; template <class Epi, class Sched, bool ALIGN_EPI = false, bool SP2 = false>
; __device__ __forceinline__ void gemm_phase(PG8_LAS unsigned char* lds, const Gemm g, const Sched& S, const Epi& E) {
;     ...
;         for (int t = 0; t < nt; t += 2) {
;             const bool last = (t == nt - 2);
;             const char* a1 = cA + (size_t)(t + 1) * kstep;
;             const char* a2 = last ? nA : cA + (size_t)(t + 2) * kstep; const char* b2 = last ? nB : cB + (size_t)(t + 2) * kstep;
;             const char* a3 = a2 + kstep; const char* b3 = b2 + kstep;
;             if (last && has_next) S.a_ready(nxt);
;             if constexpr (SP2) {
;             PG8_LDB(B0, 0, 0); PG8_LDB(B1, 0, 1); PG8_SCHED; PG8_LDA(At, 0, 0); PG8_STAGE(PG8_SA(1, 1), a1 + hstep, voffA);
;             PG8_WAIT_V(8); PG8_WAIT_L(0); PG8_BAR; PG8_MMA(0, 0, At, B0); PG8_MMA(0, 1, At, B1); PG8_BAR; PG8_SCHED;
;             PG8_LDA(At, 0, 1); PG8_STAGE(PG8_SB(0, 0), b2, voffB); PG8_STAGE(PG8_SB(0, 1), b2 + hstep, voffB); PG8_STAGE(PG8_SA(0, 0), a2, voffA);
;             PG8_WAIT_V(8); PG8_WAIT_L(0); PG8_BAR; PG8_MMA(1, 0, At, B0); PG8_MMA(1, 1, At, B1); PG8_BAR; PG8_SCHED;
.LBB0_706:
	s_add_u32 s6, s4, 0xebb40080
	s_addc_u32 s7, s5, -1
	s_cmp_lg_u32 s21, 12
	s_cselect_b32 s6, s6, 0
	s_cselect_b32 s7, s7, 0
	s_add_u32 s8, s2, s6
	s_addc_u32 s9, s3, s7
	s_add_i32 s22, 0, 0x10000
	s_add_u32 s6, s0, s6
	s_addc_u32 s7, s1, s7
	s_add_i32 s24, 0, 0x14000
	v_add_u32_e32 v154, s22, v140
	v_add_u32_e32 v170, s24, v140
	ds_read_b128 v[142:145], v154
	ds_read_b128 v[146:149], v154 offset:1024
	ds_read_b128 v[150:153], v154 offset:2048
	ds_read_b128 v[154:157], v154 offset:3072
	ds_read_b128 v[158:161], v170
	ds_read_b128 v[162:165], v170 offset:1024
	ds_read_b128 v[166:169], v170 offset:2048
	ds_read_b128 v[170:173], v170 offset:3072
	v_lshl_add_u64 v[186:187], v[134:135], 0, s[4:5]
	s_add_i32 m0, s14, 0xc000
	ds_read_b128 v[174:177], v141
	ds_read_b128 v[178:181], v141 offset:1024
	ds_read_b128 v[182:185], v141 offset:2048
	ds_read_b128 v[194:197], v141 offset:3072
	ds_read_b128 v[198:201], v141 offset:4096
	ds_read_b128 v[202:205], v141 offset:5120
	ds_read_b128 v[210:213], v141 offset:6144
	ds_read_b128 v[214:217], v141 offset:7168
	global_load_lds_dwordx4 v[186:187], off
	v_lshl_add_u64 v[186:187], v[136:137], 0, s[4:5]
	s_add_i32 m0, s14, 0xe000
	s_nop 0
	global_load_lds_dwordx4 v[186:187], off
	s_waitcnt vmcnt(8)
	s_waitcnt lgkmcnt(0)
	s_barrier
	s_setprio 1
	s_waitcnt lgkmcnt(0)
	v_mfma_f32_16x16x32_bf16 v[124:127], v[142:145], v[174:177], v[124:127]
	v_mfma_f32_16x16x32_bf16 v[120:123], v[150:153], v[174:177], v[120:123]
	v_mfma_f32_16x16x32_bf16 v[108:111], v[142:145], v[182:185], v[108:111]
	v_mfma_f32_16x16x32_bf16 v[104:107], v[150:153], v[182:185], v[104:107]
	v_mfma_f32_16x16x32_bf16 v[92:95], v[142:145], v[198:201], v[92:95]
	v_mfma_f32_16x16x32_bf16 v[88:91], v[150:153], v[198:201], v[88:91]
	v_mfma_f32_16x16x32_bf16 v[76:79], v[142:145], v[210:213], v[76:79]
	v_mfma_f32_16x16x32_bf16 v[72:75], v[150:153], v[210:213], v[72:75]
	v_mfma_f32_16x16x32_bf16 v[124:127], v[146:149], v[178:181], v[124:127]
	v_mfma_f32_16x16x32_bf16 v[120:123], v[154:157], v[178:181], v[120:123]
	v_mfma_f32_16x16x32_bf16 v[108:111], v[146:149], v[194:197], v[108:111]
	v_mfma_f32_16x16x32_bf16 v[104:107], v[154:157], v[194:197], v[104:107]
	v_mfma_f32_16x16x32_bf16 v[92:95], v[146:149], v[202:205], v[92:95]
	v_mfma_f32_16x16x32_bf16 v[88:91], v[154:157], v[202:205], v[88:91]
	v_mfma_f32_16x16x32_bf16 v[76:79], v[146:149], v[214:217], v[76:79]
	v_mfma_f32_16x16x32_bf16 v[72:75], v[154:157], v[214:217], v[72:75]
	s_setprio 0
	s_setprio 1
	v_mfma_f32_16x16x32_bf16 v[116:119], v[158:161], v[174:177], v[116:119]
	v_mfma_f32_16x16x32_bf16 v[112:115], v[166:169], v[174:177], v[112:115]
	v_mfma_f32_16x16x32_bf16 v[100:103], v[158:161], v[182:185], v[100:103]
	v_mfma_f32_16x16x32_bf16 v[96:99], v[166:169], v[182:185], v[96:99]
	v_mfma_f32_16x16x32_bf16 v[84:87], v[158:161], v[198:201], v[84:87]
	v_mfma_f32_16x16x32_bf16 v[80:83], v[166:169], v[198:201], v[80:83]
	v_mfma_f32_16x16x32_bf16 v[68:71], v[158:161], v[210:213], v[68:71]
	v_mfma_f32_16x16x32_bf16 v[64:67], v[166:169], v[210:213], v[64:67]
	v_mfma_f32_16x16x32_bf16 v[116:119], v[162:165], v[178:181], v[116:119]
	v_mfma_f32_16x16x32_bf16 v[112:115], v[170:173], v[178:181], v[112:115]
	v_mfma_f32_16x16x32_bf16 v[100:103], v[162:165], v[194:197], v[100:103]
	v_mfma_f32_16x16x32_bf16 v[96:99], v[170:173], v[194:197], v[96:99]
	v_mfma_f32_16x16x32_bf16 v[84:87], v[162:165], v[202:205], v[84:87]
	v_mfma_f32_16x16x32_bf16 v[80:83], v[170:173], v[202:205], v[80:83]
	v_mfma_f32_16x16x32_bf16 v[68:71], v[162:165], v[214:217], v[68:71]
	v_mfma_f32_16x16x32_bf16 v[64:67], v[170:173], v[214:217], v[64:67]
	s_setprio 0
	s_barrier
	s_add_i32 s22, s22, s13
	v_lshl_add_u64 v[186:187], s[6:7], 0, v[188:189]
	s_mov_b32 m0, s22
	ds_read_b128 v[174:177], v141 offset:16384
	ds_read_b128 v[178:181], v141 offset:17408
	ds_read_b128 v[182:185], v141 offset:18432
	ds_read_b128 v[194:197], v141 offset:19456
	ds_read_b128 v[198:201], v141 offset:20480
	ds_read_b128 v[202:205], v141 offset:21504
	ds_read_b128 v[210:213], v141 offset:22528
	ds_read_b128 v[214:217], v141 offset:23552
	global_load_lds_dwordx4 v[186:187], off
	s_add_i32 m0, s22, 0x2000
	s_add_u32 s22, s6, 0x40000
	v_lshl_add_u64 v[190:191], s[6:7], 0, v[132:133]
	s_addc_u32 s23, s7, 0
	s_add_i32 s24, s24, s13
	global_load_lds_dwordx4 v[190:191], off
	v_lshl_add_u64 v[218:219], s[22:23], 0, v[188:189]
	s_mov_b32 m0, s24
	v_lshl_add_u64 v[220:221], s[8:9], 0, v[130:131]
	global_load_lds_dwordx4 v[218:219], off
	v_lshl_add_u64 v[218:219], s[22:23], 0, v[132:133]
	s_add_i32 m0, s24, 0x2000
	s_nop 0
	global_load_lds_dwordx4 v[218:219], off
	v_lshl_add_u64 v[218:219], s[8:9], 0, v[128:129]
	s_mov_b32 m0, s14
	s_nop 0
	global_load_lds_dwordx4 v[218:219], off
	s_mov_b32 m0, s15
	s_nop 0
	global_load_lds_dwordx4 v[220:221], off
	s_waitcnt vmcnt(8)
	s_waitcnt lgkmcnt(0)
	s_barrier
; #define PG8_STAGE(bufoff, gbase, voff) do { _Pragma("unroll") for (int _i = 0; _i < 2; ++_i) \
;         __builtin_amdgcn_global_load_lds((const unsigned*)((const char*)(gbase) + (voff)[_i]), (PG8_LAS unsigned*)(lds + (bufoff) + ldsw + _i * 8192), 16, 0, 0); } while (0)
; #define PG8_LDA(dst, b, h) do { _Pragma("unroll") for (int m = 0; m < 4; ++m) _Pragma("unroll") for (int k = 0; k < 2; ++k) dst[m][k] = *(const PG8_LAS bf16x8*)(lds + PG8_SA(b, h) + aoff + m * 2048 + k * 1024); } while (0)
; #define PG8_LDB(dst, b, h) do { _Pragma("unroll") for (int n = 0; n < 2; ++n) _Pragma("unroll") for (int k = 0; k < 2; ++k) dst[n][k] = *(const PG8_LAS bf16x8*)(lds + PG8_SB(b, h) + boff + n * 2048 + k * 1024); } while (0)
; #define PG8_MMA(ai, bj, At, Bt) do { __builtin_amdgcn_s_setprio(1); _Pragma("unroll") for (int m = 0; m < 4; ++m) _Pragma("unroll") for (int n = 0; n < 2; ++n) _Pragma("unroll") for (int k = 0; k < 2; ++k) \
;         acc[ai][bj][m][n] = __builtin_amdgcn_mfma_f32_16x16x32_bf16(Bt[n][k], At[m][k], acc[ai][bj][m][n], 0, 0, 0); __builtin_amdgcn_s_setprio(0); } while (0)
; #define PG8_WAIT_V(n) asm volatile("s_waitcnt vmcnt(" #n ")" ::: "memory")
; #define PG8_WAIT_L(n) asm volatile("s_waitcnt lgkmcnt(" #n ")" ::: "memory")
; #define PG8_BAR __builtin_amdgcn_s_barrier()
; #define PG8_SCHED __builtin_amdgcn_sched_barrier(0)
; template <class Epi, class Sched, bool ALIGN_EPI = false, bool SP2 = false>
; __device__ __forceinline__ void gemm_phase(PG8_LAS unsigned char* lds, const Gemm g, const Sched& S, const Epi& E) {
;     ...
;             PG8_WAIT_V(8); PG8_WAIT_L(0); PG8_BAR; PG8_MMA(1, 0, At, B0); PG8_MMA(1, 1, At, B1); PG8_BAR; PG8_SCHED;
;             PG8_LDB(B0, 1, 0); PG8_LDB(B1, 1, 1); PG8_SCHED; PG8_LDA(At, 1, 0); PG8_STAGE(PG8_SA(0, 1), a2 + hstep, voffA);
;             PG8_WAIT_V(8); PG8_WAIT_L(0); PG8_BAR; PG8_MMA(0, 0, At, B0); PG8_MMA(0, 1, At, B1); PG8_BAR; PG8_SCHED;
;             PG8_LDA(At, 1, 1); PG8_STAGE(PG8_SB(1, 0), b3, voffB); PG8_STAGE(PG8_SB(1, 1), b3 + hstep, voffB); PG8_STAGE(PG8_SA(1, 0), a3, voffA);
;             PG8_WAIT_V(8); PG8_WAIT_L(0); PG8_BAR; PG8_MMA(1, 0, At, B0); PG8_MMA(1, 1, At, B1); PG8_BAR; PG8_SCHED;
	s_setprio 1
	s_waitcnt lgkmcnt(0)
	v_mfma_f32_16x16x32_bf16 v[60:63], v[142:145], v[174:177], v[60:63]
	v_mfma_f32_16x16x32_bf16 v[56:59], v[150:153], v[174:177], v[56:59]
	v_mfma_f32_16x16x32_bf16 v[44:47], v[142:145], v[182:185], v[44:47]
	v_mfma_f32_16x16x32_bf16 v[40:43], v[150:153], v[182:185], v[40:43]
	v_mfma_f32_16x16x32_bf16 v[28:31], v[142:145], v[198:201], v[28:31]
	v_mfma_f32_16x16x32_bf16 v[24:27], v[150:153], v[198:201], v[24:27]
	v_mfma_f32_16x16x32_bf16 v[12:15], v[142:145], v[210:213], v[12:15]
	v_mfma_f32_16x16x32_bf16 v[8:11], v[150:153], v[210:213], v[8:11]
	v_mfma_f32_16x16x32_bf16 v[60:63], v[146:149], v[178:181], v[60:63]
	v_mfma_f32_16x16x32_bf16 v[56:59], v[154:157], v[178:181], v[56:59]
	v_mfma_f32_16x16x32_bf16 v[44:47], v[146:149], v[194:197], v[44:47]
	v_mfma_f32_16x16x32_bf16 v[40:43], v[154:157], v[194:197], v[40:43]
	v_mfma_f32_16x16x32_bf16 v[28:31], v[146:149], v[202:205], v[28:31]
	v_mfma_f32_16x16x32_bf16 v[24:27], v[154:157], v[202:205], v[24:27]
	v_mfma_f32_16x16x32_bf16 v[12:15], v[146:149], v[214:217], v[12:15]
	v_mfma_f32_16x16x32_bf16 v[8:11], v[154:157], v[214:217], v[8:11]
	s_setprio 0
	s_setprio 1
	v_mfma_f32_16x16x32_bf16 v[52:55], v[158:161], v[174:177], v[52:55]
	v_mfma_f32_16x16x32_bf16 v[48:51], v[166:169], v[174:177], v[48:51]
	v_mfma_f32_16x16x32_bf16 v[36:39], v[158:161], v[182:185], v[36:39]
	v_mfma_f32_16x16x32_bf16 v[32:35], v[166:169], v[182:185], v[32:35]
	v_mfma_f32_16x16x32_bf16 v[20:23], v[158:161], v[198:201], v[20:23]
	v_mfma_f32_16x16x32_bf16 v[16:19], v[166:169], v[198:201], v[16:19]
	v_mfma_f32_16x16x32_bf16 v[4:7], v[158:161], v[210:213], v[4:7]
	v_mfma_f32_16x16x32_bf16 v[0:3], v[166:169], v[210:213], v[0:3]
	v_mfma_f32_16x16x32_bf16 v[52:55], v[162:165], v[178:181], v[52:55]
	v_mfma_f32_16x16x32_bf16 v[48:51], v[170:173], v[178:181], v[48:51]
	v_mfma_f32_16x16x32_bf16 v[36:39], v[162:165], v[194:197], v[36:39]
	v_mfma_f32_16x16x32_bf16 v[32:35], v[170:173], v[194:197], v[32:35]
	v_mfma_f32_16x16x32_bf16 v[20:23], v[162:165], v[202:205], v[20:23]
	v_mfma_f32_16x16x32_bf16 v[16:19], v[170:173], v[202:205], v[16:19]
	v_mfma_f32_16x16x32_bf16 v[4:7], v[162:165], v[214:217], v[4:7]
	v_mfma_f32_16x16x32_bf16 v[0:3], v[170:173], v[214:217], v[0:3]
	s_setprio 0
	s_barrier
	s_add_i32 s22, 0, 0x18000
	s_add_i32 s23, 0, 0x1c000
	v_add_u32_e32 v154, s22, v140
	v_add_u32_e32 v170, s23, v140
	ds_read_b128 v[142:145], v154
	ds_read_b128 v[146:149], v154 offset:1024
	ds_read_b128 v[150:153], v154 offset:2048
	ds_read_b128 v[154:157], v154 offset:3072
	ds_read_b128 v[158:161], v170
	ds_read_b128 v[162:165], v170 offset:1024
	ds_read_b128 v[166:169], v170 offset:2048
	ds_read_b128 v[170:173], v170 offset:3072
	s_add_u32 s8, s8, 0x40000
	s_addc_u32 s9, s9, 0
	s_mov_b32 m0, s16
	v_lshl_add_u64 v[222:223], s[8:9], 0, v[128:129]
	ds_read_b128 v[174:177], v141 offset:32768
	ds_read_b128 v[178:181], v141 offset:33792
	ds_read_b128 v[182:185], v141 offset:34816
	ds_read_b128 v[194:197], v141 offset:35840
	ds_read_b128 v[198:201], v141 offset:36864
	ds_read_b128 v[202:205], v141 offset:37888
	ds_read_b128 v[210:213], v141 offset:38912
	ds_read_b128 v[214:217], v141 offset:39936
	global_load_lds_dwordx4 v[222:223], off
	v_lshl_add_u64 v[222:223], s[8:9], 0, v[130:131]
	s_mov_b32 m0, s17
	s_nop 0
	global_load_lds_dwordx4 v[222:223], off
	s_waitcnt vmcnt(8)
	s_waitcnt lgkmcnt(0)
	s_barrier
	s_setprio 1
	s_waitcnt lgkmcnt(0)
	v_mfma_f32_16x16x32_bf16 v[124:127], v[142:145], v[174:177], v[124:127]
	v_mfma_f32_16x16x32_bf16 v[120:123], v[150:153], v[174:177], v[120:123]
	v_mfma_f32_16x16x32_bf16 v[108:111], v[142:145], v[182:185], v[108:111]
	v_mfma_f32_16x16x32_bf16 v[104:107], v[150:153], v[182:185], v[104:107]
	v_mfma_f32_16x16x32_bf16 v[92:95], v[142:145], v[198:201], v[92:95]
	v_mfma_f32_16x16x32_bf16 v[88:91], v[150:153], v[198:201], v[88:91]
	v_mfma_f32_16x16x32_bf16 v[76:79], v[142:145], v[210:213], v[76:79]
	v_mfma_f32_16x16x32_bf16 v[72:75], v[150:153], v[210:213], v[72:75]
	v_mfma_f32_16x16x32_bf16 v[124:127], v[146:149], v[178:181], v[124:127]
	v_mfma_f32_16x16x32_bf16 v[120:123], v[154:157], v[178:181], v[120:123]
	v_mfma_f32_16x16x32_bf16 v[108:111], v[146:149], v[194:197], v[108:111]
	v_mfma_f32_16x16x32_bf16 v[104:107], v[154:157], v[194:197], v[104:107]
	v_mfma_f32_16x16x32_bf16 v[92:95], v[146:149], v[202:205], v[92:95]
	v_mfma_f32_16x16x32_bf16 v[88:91], v[154:157], v[202:205], v[88:91]
	v_mfma_f32_16x16x32_bf16 v[76:79], v[146:149], v[214:217], v[76:79]
	v_mfma_f32_16x16x32_bf16 v[72:75], v[154:157], v[214:217], v[72:75]
	s_setprio 0
	s_setprio 1
	v_mfma_f32_16x16x32_bf16 v[116:119], v[158:161], v[174:177], v[116:119]
	v_mfma_f32_16x16x32_bf16 v[112:115], v[166:169], v[174:177], v[112:115]
	v_mfma_f32_16x16x32_bf16 v[100:103], v[158:161], v[182:185], v[100:103]
	v_mfma_f32_16x16x32_bf16 v[96:99], v[166:169], v[182:185], v[96:99]
	v_mfma_f32_16x16x32_bf16 v[84:87], v[158:161], v[198:201], v[84:87]
	v_mfma_f32_16x16x32_bf16 v[80:83], v[166:169], v[198:201], v[80:83]
	v_mfma_f32_16x16x32_bf16 v[68:71], v[158:161], v[210:213], v[68:71]
	v_mfma_f32_16x16x32_bf16 v[64:67], v[166:169], v[210:213], v[64:67]
	v_mfma_f32_16x16x32_bf16 v[116:119], v[162:165], v[178:181], v[116:119]
	v_mfma_f32_16x16x32_bf16 v[112:115], v[170:173], v[178:181], v[112:115]
	v_mfma_f32_16x16x32_bf16 v[100:103], v[162:165], v[194:197], v[100:103]
	v_mfma_f32_16x16x32_bf16 v[96:99], v[170:173], v[194:197], v[96:99]
	v_mfma_f32_16x16x32_bf16 v[84:87], v[162:165], v[202:205], v[84:87]
	v_mfma_f32_16x16x32_bf16 v[80:83], v[170:173], v[202:205], v[80:83]
	v_mfma_f32_16x16x32_bf16 v[68:71], v[162:165], v[214:217], v[68:71]
	v_mfma_f32_16x16x32_bf16 v[64:67], v[170:173], v[214:217], v[64:67]
	s_setprio 0
	s_barrier
; #define PG8_STAGE(bufoff, gbase, voff) do { _Pragma("unroll") for (int _i = 0; _i < 2; ++_i) \
;         __builtin_amdgcn_global_load_lds((const unsigned*)((const char*)(gbase) + (voff)[_i]), (PG8_LAS unsigned*)(lds + (bufoff) + ldsw + _i * 8192), 16, 0, 0); } while (0)
; #define PG8_LDA(dst, b, h) do { _Pragma("unroll") for (int m = 0; m < 4; ++m) _Pragma("unroll") for (int k = 0; k < 2; ++k) dst[m][k] = *(const PG8_LAS bf16x8*)(lds + PG8_SA(b, h) + aoff + m * 2048 + k * 1024); } while (0)
; #define PG8_MMA(ai, bj, At, Bt) do { __builtin_amdgcn_s_setprio(1); _Pragma("unroll") for (int m = 0; m < 4; ++m) _Pragma("unroll") for (int n = 0; n < 2; ++n) _Pragma("unroll") for (int k = 0; k < 2; ++k) \
;         acc[ai][bj][m][n] = __builtin_amdgcn_mfma_f32_16x16x32_bf16(Bt[n][k], At[m][k], acc[ai][bj][m][n], 0, 0, 0); __builtin_amdgcn_s_setprio(0); } while (0)
; #define PG8_WAIT_V(n) asm volatile("s_waitcnt vmcnt(" #n ")" ::: "memory")
; #define PG8_WAIT_L(n) asm volatile("s_waitcnt lgkmcnt(" #n ")" ::: "memory")
; #define PG8_BAR __builtin_amdgcn_s_barrier()
; #define PG8_SCHED __builtin_amdgcn_sched_barrier(0)
;     __device__ __forceinline__ void operator()(const f32x4 (&acc)[2][2][4][2], const Unit& u, int wr, int wc, int fr, int fq) const {
;         const int row0 = u.pm * BM + wr * 64 + fr; const size_t col0 = (size_t)u.pn * BM + wc * 32 + 8 * fq;
; #pragma unroll
;         for (int ai = 0; ai < 2; ++ai)
; #pragma unroll
;             for (int m = 0; m < 4; ++m) { const size_t off = (size_t)(row0 + ai * HALF + m * 16) * 1024 + col0;
; #pragma unroll
;                 for (int bj = 0; bj < 2; ++bj) { const u32x4 gw = *(const u32x4*)(Gt + off + bj * HALF);
; template <class Epi, class Sched, bool ALIGN_EPI = false, bool SP2 = false>
; __device__ __forceinline__ void gemm_phase(PG8_LAS unsigned char* lds, const Gemm g, const Sched& S, const Epi& E) {
;     ...
;             PG8_LDA(At, 1, 1); PG8_STAGE(PG8_SB(1, 0), b3, voffB); PG8_STAGE(PG8_SB(1, 1), b3 + hstep, voffB); PG8_STAGE(PG8_SA(1, 0), a3, voffA);
;             PG8_WAIT_V(8); PG8_WAIT_L(0); PG8_BAR; PG8_MMA(1, 0, At, B0); PG8_MMA(1, 1, At, B1); PG8_BAR; PG8_SCHED;
	s_add_i32 s8, s22, s13
	v_lshl_add_u64 v[186:187], v[186:187], 0, s[26:27]
	s_mov_b32 m0, s8
	ds_read_b128 v[174:177], v141 offset:49152
	ds_read_b128 v[178:181], v141 offset:50176
	ds_read_b128 v[182:185], v141 offset:51200
	ds_read_b128 v[194:197], v141 offset:52224
	ds_read_b128 v[198:201], v141 offset:53248
	ds_read_b128 v[202:205], v141 offset:54272
	ds_read_b128 v[210:213], v141 offset:55296
	ds_read_b128 v[214:217], v141 offset:56320
	global_load_lds_dwordx4 v[186:187], off
	s_add_i32 m0, s8, 0x2000
	s_add_u32 s6, s6, 0x40080
	v_lshl_add_u64 v[186:187], v[190:191], 0, s[26:27]
	s_addc_u32 s7, s7, 0
	s_add_i32 s8, s23, s13
	global_load_lds_dwordx4 v[186:187], off
	v_lshl_add_u64 v[186:187], s[6:7], 0, v[188:189]
	s_mov_b32 m0, s8
	s_nop 0
	global_load_lds_dwordx4 v[186:187], off
	v_lshl_add_u64 v[186:187], s[6:7], 0, v[132:133]
	s_add_i32 m0, s8, 0x2000
	s_nop 0
	global_load_lds_dwordx4 v[186:187], off
	v_lshl_add_u64 v[186:187], v[218:219], 0, s[26:27]
	s_mov_b32 m0, s19
	s_nop 0
	global_load_lds_dwordx4 v[186:187], off
	v_lshl_add_u64 v[186:187], v[220:221], 0, s[26:27]
	s_mov_b32 m0, s20
	s_nop 0
	global_load_lds_dwordx4 v[186:187], off
	s_waitcnt vmcnt(8)
	s_waitcnt lgkmcnt(0)
	s_barrier
	s_setprio 1
	s_waitcnt lgkmcnt(0)
	v_mfma_f32_16x16x32_bf16 v[60:63], v[142:145], v[174:177], v[60:63]
	v_mfma_f32_16x16x32_bf16 v[56:59], v[150:153], v[174:177], v[56:59]
	v_mfma_f32_16x16x32_bf16 v[44:47], v[142:145], v[182:185], v[44:47]
	v_mfma_f32_16x16x32_bf16 v[40:43], v[150:153], v[182:185], v[40:43]
	v_mfma_f32_16x16x32_bf16 v[28:31], v[142:145], v[198:201], v[28:31]
	v_mfma_f32_16x16x32_bf16 v[24:27], v[150:153], v[198:201], v[24:27]
	v_mfma_f32_16x16x32_bf16 v[12:15], v[142:145], v[210:213], v[12:15]
	v_mfma_f32_16x16x32_bf16 v[8:11], v[150:153], v[210:213], v[8:11]
	v_mfma_f32_16x16x32_bf16 v[60:63], v[146:149], v[178:181], v[60:63]
	v_mfma_f32_16x16x32_bf16 v[56:59], v[154:157], v[178:181], v[56:59]
	v_mfma_f32_16x16x32_bf16 v[44:47], v[146:149], v[194:197], v[44:47]
	v_mfma_f32_16x16x32_bf16 v[40:43], v[154:157], v[194:197], v[40:43]
	v_mfma_f32_16x16x32_bf16 v[28:31], v[146:149], v[202:205], v[28:31]
	v_mfma_f32_16x16x32_bf16 v[24:27], v[154:157], v[202:205], v[24:27]
	v_mfma_f32_16x16x32_bf16 v[12:15], v[146:149], v[214:217], v[12:15]
	v_mfma_f32_16x16x32_bf16 v[8:11], v[154:157], v[214:217], v[8:11]
	s_setprio 0
	s_setprio 1
	v_mfma_f32_16x16x32_bf16 v[52:55], v[158:161], v[174:177], v[52:55]
	v_mfma_f32_16x16x32_bf16 v[48:51], v[166:169], v[174:177], v[48:51]
	v_mfma_f32_16x16x32_bf16 v[36:39], v[158:161], v[182:185], v[36:39]
	v_mfma_f32_16x16x32_bf16 v[32:35], v[166:169], v[182:185], v[32:35]
	v_mfma_f32_16x16x32_bf16 v[20:23], v[158:161], v[198:201], v[20:23]
	v_mfma_f32_16x16x32_bf16 v[16:19], v[166:169], v[198:201], v[16:19]
	v_mfma_f32_16x16x32_bf16 v[4:7], v[158:161], v[210:213], v[4:7]
	v_mfma_f32_16x16x32_bf16 v[0:3], v[166:169], v[210:213], v[0:3]
	v_mfma_f32_16x16x32_bf16 v[52:55], v[162:165], v[178:181], v[52:55]
	v_mfma_f32_16x16x32_bf16 v[48:51], v[170:173], v[178:181], v[48:51]
	v_mfma_f32_16x16x32_bf16 v[36:39], v[162:165], v[194:197], v[36:39]
	v_mfma_f32_16x16x32_bf16 v[32:35], v[170:173], v[194:197], v[32:35]
	v_mfma_f32_16x16x32_bf16 v[20:23], v[162:165], v[202:205], v[20:23]
	v_mfma_f32_16x16x32_bf16 v[16:19], v[170:173], v[202:205], v[16:19]
	v_mfma_f32_16x16x32_bf16 v[4:7], v[162:165], v[214:217], v[4:7]
	v_mfma_f32_16x16x32_bf16 v[0:3], v[170:173], v[214:217], v[0:3]
	s_setprio 0
	s_barrier
	s_add_i32 s21, s21, 2
	s_add_u32 s4, s4, 0x100
	s_addc_u32 s5, s5, 0
	s_cmp_gt_u32 s21, 13
	s_cbranch_scc0 .LBB0_706
	v_lshl_add_u32 v128, s11, 8, v138
	v_or_b32_e32 v129, s18, v139
	v_lshlrev_b32_e32 v128, 11, v128
	v_lshl_add_u32 v128, v129, 1, v128
	s_lshl_b32 s4, s12, 9
	v_add_u32_e32 v128, s4, v128
	v_readlane_b32 s2, v254, 42
	v_readlane_b32 s3, v254, 43
	v_readlane_b32 s0, v254, 21
	v_readlane_b32 s1, v254, 22
	s_mov_b64 s[4:5], s[2:3]
	global_load_dwordx4 v[142:145], v128, s[4:5]
	global_load_dwordx4 v[146:149], v128, s[4:5] offset:256
	s_add_u32 s4, s2, 0x8000
	s_addc_u32 s5, s3, 0
	global_load_dwordx4 v[150:153], v128, s[4:5]
	global_load_dwordx4 v[154:157], v128, s[4:5] offset:256
	s_add_u32 s4, s2, 0x10000
	s_addc_u32 s5, s3, 0
	global_load_dwordx4 v[158:161], v128, s[4:5]
	global_load_dwordx4 v[162:165], v128, s[4:5] offset:256
	s_add_u32 s4, s2, 0x18000
	s_addc_u32 s5, s3, 0
	global_load_dwordx4 v[166:169], v128, s[4:5]
	global_load_dwordx4 v[170:173], v128, s[4:5] offset:256
	s_add_u32 s4, s2, 0x40000
	s_addc_u32 s5, s3, 0
	global_load_dwordx4 v[174:177], v128, s[4:5]
	global_load_dwordx4 v[178:181], v128, s[4:5] offset:256
	s_add_u32 s4, s2, 0x48000
	s_addc_u32 s5, s3, 0
	global_load_dwordx4 v[182:185], v128, s[4:5]
	global_load_dwordx4 v[194:197], v128, s[4:5] offset:256
	s_add_u32 s4, s2, 0x50000
	s_addc_u32 s5, s3, 0
	global_load_dwordx4 v[198:201], v128, s[4:5]
	global_load_dwordx4 v[202:205], v128, s[4:5] offset:256
	s_add_u32 s4, s2, 0x58000
	s_addc_u32 s5, s3, 0
	global_load_dwordx4 v[210:213], v128, s[4:5]
	global_load_dwordx4 v[214:217], v128, s[4:5] offset:256
	s_cmpk_lt_u32 s10, 0x100
	s_cbranch_scc0 .LBB0_709
	s_barrier
; __device__ __forceinline__ u32x4 pack8(const f32x4 a, const f32x4 b) { u32x4 w; w.x = cvt_pk_bf16(a[0], a[1]); w.y = cvt_pk_bf16(a[2], a[3]); w.z = cvt_pk_bf16(b[0], b[1]); w.w = cvt_pk_bf16(b[2], b[3]); return w; }
;     __device__ __forceinline__ void operator()(const f32x4 (&acc)[2][2][4][2], const Unit& u, int wr, int wc, int fr, int fq) const {
;         const int row0 = u.pm * BM + wr * 64 + fr; const size_t col0 = (size_t)u.pn * BM + wc * 32 + 8 * fq;
; #pragma unroll
;         for (int ai = 0; ai < 2; ++ai)
; #pragma unroll
;             for (int m = 0; m < 4; ++m) { const size_t off = (size_t)(row0 + ai * HALF + m * 16) * 1024 + col0;
; #pragma unroll
;                 for (int bj = 0; bj < 2; ++bj) { const u32x4 gw = *(const u32x4*)(Gt + off + bj * HALF);
;                     f32x4 v0 = acc[ai][bj][m][0], v1 = acc[ai][bj][m][1];
;                     v0[0] *= bflo(gw.x); v0[1] *= bfhi(gw.x); v0[2] *= bflo(gw.y); v0[3] *= bfhi(gw.y);
;                     v1[0] *= bflo(gw.z); v1[1] *= bfhi(gw.z); v1[2] *= bflo(gw.w); v1[3] *= bfhi(gw.w);
;                     if (ADD) { const u32x4 pw = *(const u32x4*)(MG + off + bj * HALF);
;                         v0[0] += bflo(pw.x); v0[1] += bfhi(pw.x); v0[2] += bflo(pw.y); v0[3] += bfhi(pw.y);
;                         v1[0] += bflo(pw.z); v1[1] += bfhi(pw.z); v1[2] += bflo(pw.w); v1[3] += bfhi(pw.w); }
;                     *(u32x4*)(MG + off + bj * HALF) = pack8(v0, v1); }
;                 asm volatile("" ::: "memory"); }
.LBB0_709:
	s_mov_b64 s[4:5], s[0:1]
	s_waitcnt vmcnt(15)
	v_lshlrev_b32_e32 v129, 16, v142
	v_and_b32_e32 v142, 0xffff0000, v142
	v_mul_f32_e32 v124, v124, v129
	v_mul_f32_e32 v125, v125, v142
	v_lshlrev_b32_e32 v129, 16, v143
	v_and_b32_e32 v143, 0xffff0000, v143
	v_mul_f32_e32 v126, v126, v129
	v_mul_f32_e32 v127, v127, v143
	v_lshlrev_b32_e32 v129, 16, v144
	v_and_b32_e32 v144, 0xffff0000, v144
	v_mul_f32_e32 v120, v120, v129
	v_mul_f32_e32 v121, v121, v144
	v_lshlrev_b32_e32 v129, 16, v145
	v_and_b32_e32 v145, 0xffff0000, v145
	v_mul_f32_e32 v122, v122, v129
	v_mul_f32_e32 v123, v123, v145
	v_cvt_pk_bf16_f32 v142, v124, v125
	v_cvt_pk_bf16_f32 v143, v126, v127
	v_cvt_pk_bf16_f32 v144, v120, v121
	v_cvt_pk_bf16_f32 v145, v122, v123
	global_store_dwordx4 v128, v[142:145], s[4:5]
	s_waitcnt vmcnt(15)
	v_lshlrev_b32_e32 v129, 16, v146
	v_and_b32_e32 v146, 0xffff0000, v146
	v_mul_f32_e32 v116, v116, v129
	v_mul_f32_e32 v117, v117, v146
	v_lshlrev_b32_e32 v129, 16, v147
	v_and_b32_e32 v147, 0xffff0000, v147
	v_mul_f32_e32 v118, v118, v129
	v_mul_f32_e32 v119, v119, v147
	v_lshlrev_b32_e32 v129, 16, v148
	v_and_b32_e32 v148, 0xffff0000, v148
	v_mul_f32_e32 v112, v112, v129
	v_mul_f32_e32 v113, v113, v148
	v_lshlrev_b32_e32 v129, 16, v149
	v_and_b32_e32 v149, 0xffff0000, v149
	v_mul_f32_e32 v114, v114, v129
	v_mul_f32_e32 v115, v115, v149
	v_cvt_pk_bf16_f32 v146, v116, v117
	v_cvt_pk_bf16_f32 v147, v118, v119
	v_cvt_pk_bf16_f32 v148, v112, v113
	v_cvt_pk_bf16_f32 v149, v114, v115
	global_store_dwordx4 v128, v[146:149], s[4:5] offset:256
	s_add_u32 s4, s0, 0x8000
	s_addc_u32 s5, s1, 0
	s_waitcnt vmcnt(15)
	v_lshlrev_b32_e32 v129, 16, v150
	v_and_b32_e32 v150, 0xffff0000, v150
	v_mul_f32_e32 v108, v108, v129
	v_mul_f32_e32 v109, v109, v150
	v_lshlrev_b32_e32 v129, 16, v151
	v_and_b32_e32 v151, 0xffff0000, v151
	v_mul_f32_e32 v110, v110, v129
	v_mul_f32_e32 v111, v111, v151
	v_lshlrev_b32_e32 v129, 16, v152
	v_and_b32_e32 v152, 0xffff0000, v152
	v_mul_f32_e32 v104, v104, v129
	v_mul_f32_e32 v105, v105, v152
	v_lshlrev_b32_e32 v129, 16, v153
	v_and_b32_e32 v153, 0xffff0000, v153
	v_mul_f32_e32 v106, v106, v129
	v_mul_f32_e32 v107, v107, v153
	v_cvt_pk_bf16_f32 v150, v108, v109
	v_cvt_pk_bf16_f32 v151, v110, v111
	v_cvt_pk_bf16_f32 v152, v104, v105
	v_cvt_pk_bf16_f32 v153, v106, v107
	global_store_dwordx4 v128, v[150:153], s[4:5]
	s_waitcnt vmcnt(15)
	v_lshlrev_b32_e32 v129, 16, v154
	v_and_b32_e32 v154, 0xffff0000, v154
	v_mul_f32_e32 v100, v100, v129
	v_mul_f32_e32 v101, v101, v154
	v_lshlrev_b32_e32 v129, 16, v155
	v_and_b32_e32 v155, 0xffff0000, v155
	v_mul_f32_e32 v102, v102, v129
	v_mul_f32_e32 v103, v103, v155
	v_lshlrev_b32_e32 v129, 16, v156
	v_and_b32_e32 v156, 0xffff0000, v156
	v_mul_f32_e32 v96, v96, v129
	v_mul_f32_e32 v97, v97, v156
	v_lshlrev_b32_e32 v129, 16, v157
	v_and_b32_e32 v157, 0xffff0000, v157
	v_mul_f32_e32 v98, v98, v129
	v_mul_f32_e32 v99, v99, v157
	v_cvt_pk_bf16_f32 v154, v100, v101
	v_cvt_pk_bf16_f32 v155, v102, v103
	v_cvt_pk_bf16_f32 v156, v96, v97
	v_cvt_pk_bf16_f32 v157, v98, v99
	global_store_dwordx4 v128, v[154:157], s[4:5] offset:256
	s_add_u32 s4, s0, 0x10000
	s_addc_u32 s5, s1, 0
	s_waitcnt vmcnt(15)
	v_lshlrev_b32_e32 v129, 16, v158
	v_and_b32_e32 v158, 0xffff0000, v158
	v_mul_f32_e32 v92, v92, v129
	v_mul_f32_e32 v93, v93, v158
	v_lshlrev_b32_e32 v129, 16, v159
	v_and_b32_e32 v159, 0xffff0000, v159
	v_mul_f32_e32 v94, v94, v129
	v_mul_f32_e32 v95, v95, v159
	v_lshlrev_b32_e32 v129, 16, v160
	v_and_b32_e32 v160, 0xffff0000, v160
	v_mul_f32_e32 v88, v88, v129
	v_mul_f32_e32 v89, v89, v160
	v_lshlrev_b32_e32 v129, 16, v161
	v_and_b32_e32 v161, 0xffff0000, v161
	v_mul_f32_e32 v90, v90, v129
	v_mul_f32_e32 v91, v91, v161
	v_cvt_pk_bf16_f32 v158, v92, v93
	v_cvt_pk_bf16_f32 v159, v94, v95
	v_cvt_pk_bf16_f32 v160, v88, v89
	v_cvt_pk_bf16_f32 v161, v90, v91
	global_store_dwordx4 v128, v[158:161], s[4:5]
	s_waitcnt vmcnt(15)
	v_lshlrev_b32_e32 v129, 16, v162
	v_and_b32_e32 v162, 0xffff0000, v162
	v_mul_f32_e32 v84, v84, v129
	v_mul_f32_e32 v85, v85, v162
	v_lshlrev_b32_e32 v129, 16, v163
	v_and_b32_e32 v163, 0xffff0000, v163
	v_mul_f32_e32 v86, v86, v129
	v_mul_f32_e32 v87, v87, v163
	v_lshlrev_b32_e32 v129, 16, v164
	v_and_b32_e32 v164, 0xffff0000, v164
	v_mul_f32_e32 v80, v80, v129
	v_mul_f32_e32 v81, v81, v164
	v_lshlrev_b32_e32 v129, 16, v165
	v_and_b32_e32 v165, 0xffff0000, v165
	v_mul_f32_e32 v82, v82, v129
	v_mul_f32_e32 v83, v83, v165
	v_cvt_pk_bf16_f32 v162, v84, v85
	v_cvt_pk_bf16_f32 v163, v86, v87
	v_cvt_pk_bf16_f32 v164, v80, v81
	v_cvt_pk_bf16_f32 v165, v82, v83
	global_store_dwordx4 v128, v[162:165], s[4:5] offset:256
	s_add_u32 s4, s0, 0x18000
	s_addc_u32 s5, s1, 0
	s_waitcnt vmcnt(15)
	v_lshlrev_b32_e32 v129, 16, v166
	v_and_b32_e32 v166, 0xffff0000, v166
	v_mul_f32_e32 v76, v76, v129
	v_mul_f32_e32 v77, v77, v166
	v_lshlrev_b32_e32 v129, 16, v167
	v_and_b32_e32 v167, 0xffff0000, v167
	v_mul_f32_e32 v78, v78, v129
	v_mul_f32_e32 v79, v79, v167
	v_lshlrev_b32_e32 v129, 16, v168
	v_and_b32_e32 v168, 0xffff0000, v168
	v_mul_f32_e32 v72, v72, v129
	v_mul_f32_e32 v73, v73, v168
	v_lshlrev_b32_e32 v129, 16, v169
	v_and_b32_e32 v169, 0xffff0000, v169
	v_mul_f32_e32 v74, v74, v129
	v_mul_f32_e32 v75, v75, v169
	v_cvt_pk_bf16_f32 v166, v76, v77
	v_cvt_pk_bf16_f32 v167, v78, v79
	v_cvt_pk_bf16_f32 v168, v72, v73
	v_cvt_pk_bf16_f32 v169, v74, v75
	global_store_dwordx4 v128, v[166:169], s[4:5]
	s_waitcnt vmcnt(15)
; __device__ __forceinline__ u32x4 pack8(const f32x4 a, const f32x4 b) { u32x4 w; w.x = cvt_pk_bf16(a[0], a[1]); w.y = cvt_pk_bf16(a[2], a[3]); w.z = cvt_pk_bf16(b[0], b[1]); w.w = cvt_pk_bf16(b[2], b[3]); return w; }
; #define PG8_WAIT_V(n) asm volatile("s_waitcnt vmcnt(" #n ")" ::: "memory")
; #define PG8_BAR __builtin_amdgcn_s_barrier()
;     __device__ __forceinline__ void operator()(const f32x4 (&acc)[2][2][4][2], const Unit& u, int wr, int wc, int fr, int fq) const {
;     ...
;             for (int m = 0; m < 4; ++m) { const size_t off = (size_t)(row0 + ai * HALF + m * 16) * 1024 + col0;
; #pragma unroll
;                 for (int bj = 0; bj < 2; ++bj) { const u32x4 gw = *(const u32x4*)(Gt + off + bj * HALF);
;                     f32x4 v0 = acc[ai][bj][m][0], v1 = acc[ai][bj][m][1];
;                     v0[0] *= bflo(gw.x); v0[1] *= bfhi(gw.x); v0[2] *= bflo(gw.y); v0[3] *= bfhi(gw.y);
;                     v1[0] *= bflo(gw.z); v1[1] *= bfhi(gw.z); v1[2] *= bflo(gw.w); v1[3] *= bfhi(gw.w);
;                     if (ADD) { const u32x4 pw = *(const u32x4*)(MG + off + bj * HALF);
;                         v0[0] += bflo(pw.x); v0[1] += bfhi(pw.x); v0[2] += bflo(pw.y); v0[3] += bfhi(pw.y);
;                         v1[0] += bflo(pw.z); v1[1] += bfhi(pw.z); v1[2] += bflo(pw.w); v1[3] += bfhi(pw.w); }
;                     *(u32x4*)(MG + off + bj * HALF) = pack8(v0, v1); }
;                 asm volatile("" ::: "memory"); }
; template <class Epi, class Sched, bool ALIGN_EPI = false, bool SP2 = false>
; __device__ __forceinline__ void gemm_phase(PG8_LAS unsigned char* lds, const Gemm g, const Sched& S, const Epi& E) {
;     ...
;     PG8_WAIT_V(0);
;     if constexpr (!ALIGN_EPI) { if (wr == 0) PG8_BAR; }
;     PG8_BAR;
	v_lshlrev_b32_e32 v129, 16, v170
	v_and_b32_e32 v170, 0xffff0000, v170
	v_mul_f32_e32 v68, v68, v129
	v_mul_f32_e32 v69, v69, v170
	v_lshlrev_b32_e32 v129, 16, v171
	v_and_b32_e32 v171, 0xffff0000, v171
	v_mul_f32_e32 v70, v70, v129
	v_mul_f32_e32 v71, v71, v171
	v_lshlrev_b32_e32 v129, 16, v172
	v_and_b32_e32 v172, 0xffff0000, v172
	v_mul_f32_e32 v64, v64, v129
	v_mul_f32_e32 v65, v65, v172
	v_lshlrev_b32_e32 v129, 16, v173
	v_and_b32_e32 v173, 0xffff0000, v173
	v_mul_f32_e32 v66, v66, v129
	v_mul_f32_e32 v67, v67, v173
	v_cvt_pk_bf16_f32 v170, v68, v69
	v_cvt_pk_bf16_f32 v171, v70, v71
	v_cvt_pk_bf16_f32 v172, v64, v65
	v_cvt_pk_bf16_f32 v173, v66, v67
	global_store_dwordx4 v128, v[170:173], s[4:5] offset:256
	s_add_u32 s4, s0, 0x40000
	s_addc_u32 s5, s1, 0
	s_waitcnt vmcnt(15)
	v_lshlrev_b32_e32 v129, 16, v174
	v_and_b32_e32 v174, 0xffff0000, v174
	v_mul_f32_e32 v60, v60, v129
	v_mul_f32_e32 v61, v61, v174
	v_lshlrev_b32_e32 v129, 16, v175
	v_and_b32_e32 v175, 0xffff0000, v175
	v_mul_f32_e32 v62, v62, v129
	v_mul_f32_e32 v63, v63, v175
	v_lshlrev_b32_e32 v129, 16, v176
	v_and_b32_e32 v176, 0xffff0000, v176
	v_mul_f32_e32 v56, v56, v129
	v_mul_f32_e32 v57, v57, v176
	v_lshlrev_b32_e32 v129, 16, v177
	v_and_b32_e32 v177, 0xffff0000, v177
	v_mul_f32_e32 v58, v58, v129
	v_mul_f32_e32 v59, v59, v177
	v_cvt_pk_bf16_f32 v174, v60, v61
	v_cvt_pk_bf16_f32 v175, v62, v63
	v_cvt_pk_bf16_f32 v176, v56, v57
	v_cvt_pk_bf16_f32 v177, v58, v59
	global_store_dwordx4 v128, v[174:177], s[4:5]
	s_waitcnt vmcnt(15)
	v_lshlrev_b32_e32 v129, 16, v178
	v_and_b32_e32 v178, 0xffff0000, v178
	v_mul_f32_e32 v52, v52, v129
	v_mul_f32_e32 v53, v53, v178
	v_lshlrev_b32_e32 v129, 16, v179
	v_and_b32_e32 v179, 0xffff0000, v179
	v_mul_f32_e32 v54, v54, v129
	v_mul_f32_e32 v55, v55, v179
	v_lshlrev_b32_e32 v129, 16, v180
	v_and_b32_e32 v180, 0xffff0000, v180
	v_mul_f32_e32 v48, v48, v129
	v_mul_f32_e32 v49, v49, v180
	v_lshlrev_b32_e32 v129, 16, v181
	v_and_b32_e32 v181, 0xffff0000, v181
	v_mul_f32_e32 v50, v50, v129
	v_mul_f32_e32 v51, v51, v181
	v_cvt_pk_bf16_f32 v178, v52, v53
	v_cvt_pk_bf16_f32 v179, v54, v55
	v_cvt_pk_bf16_f32 v180, v48, v49
	v_cvt_pk_bf16_f32 v181, v50, v51
	global_store_dwordx4 v128, v[178:181], s[4:5] offset:256
	s_add_u32 s4, s0, 0x48000
	s_addc_u32 s5, s1, 0
	s_waitcnt vmcnt(15)
	v_lshlrev_b32_e32 v129, 16, v182
	v_and_b32_e32 v182, 0xffff0000, v182
	v_mul_f32_e32 v44, v44, v129
	v_mul_f32_e32 v45, v45, v182
	v_lshlrev_b32_e32 v129, 16, v183
	v_and_b32_e32 v183, 0xffff0000, v183
	v_mul_f32_e32 v46, v46, v129
	v_mul_f32_e32 v47, v47, v183
	v_lshlrev_b32_e32 v129, 16, v184
	v_and_b32_e32 v184, 0xffff0000, v184
	v_mul_f32_e32 v40, v40, v129
	v_mul_f32_e32 v41, v41, v184
	v_lshlrev_b32_e32 v129, 16, v185
	v_and_b32_e32 v185, 0xffff0000, v185
	v_mul_f32_e32 v42, v42, v129
	v_mul_f32_e32 v43, v43, v185
	v_cvt_pk_bf16_f32 v182, v44, v45
	v_cvt_pk_bf16_f32 v183, v46, v47
	v_cvt_pk_bf16_f32 v184, v40, v41
	v_cvt_pk_bf16_f32 v185, v42, v43
	global_store_dwordx4 v128, v[182:185], s[4:5]
	s_waitcnt vmcnt(15)
	v_lshlrev_b32_e32 v129, 16, v194
	v_and_b32_e32 v194, 0xffff0000, v194
	v_mul_f32_e32 v36, v36, v129
	v_mul_f32_e32 v37, v37, v194
	v_lshlrev_b32_e32 v129, 16, v195
	v_and_b32_e32 v195, 0xffff0000, v195
	v_mul_f32_e32 v38, v38, v129
	v_mul_f32_e32 v39, v39, v195
	v_lshlrev_b32_e32 v129, 16, v196
	v_and_b32_e32 v196, 0xffff0000, v196
	v_mul_f32_e32 v32, v32, v129
	v_mul_f32_e32 v33, v33, v196
	v_lshlrev_b32_e32 v129, 16, v197
	v_and_b32_e32 v197, 0xffff0000, v197
	v_mul_f32_e32 v34, v34, v129
	v_mul_f32_e32 v35, v35, v197
	v_cvt_pk_bf16_f32 v194, v36, v37
	v_cvt_pk_bf16_f32 v195, v38, v39
	v_cvt_pk_bf16_f32 v196, v32, v33
	v_cvt_pk_bf16_f32 v197, v34, v35
	global_store_dwordx4 v128, v[194:197], s[4:5] offset:256
	s_add_u32 s4, s0, 0x50000
	s_addc_u32 s5, s1, 0
	s_waitcnt vmcnt(15)
	v_lshlrev_b32_e32 v129, 16, v198
	v_and_b32_e32 v198, 0xffff0000, v198
	v_mul_f32_e32 v28, v28, v129
	v_mul_f32_e32 v29, v29, v198
	v_lshlrev_b32_e32 v129, 16, v199
	v_and_b32_e32 v199, 0xffff0000, v199
	v_mul_f32_e32 v30, v30, v129
	v_mul_f32_e32 v31, v31, v199
	v_lshlrev_b32_e32 v129, 16, v200
	v_and_b32_e32 v200, 0xffff0000, v200
	v_mul_f32_e32 v24, v24, v129
	v_mul_f32_e32 v25, v25, v200
	v_lshlrev_b32_e32 v129, 16, v201
	v_and_b32_e32 v201, 0xffff0000, v201
	v_mul_f32_e32 v26, v26, v129
	v_mul_f32_e32 v27, v27, v201
	v_cvt_pk_bf16_f32 v198, v28, v29
	v_cvt_pk_bf16_f32 v199, v30, v31
	v_cvt_pk_bf16_f32 v200, v24, v25
	v_cvt_pk_bf16_f32 v201, v26, v27
	global_store_dwordx4 v128, v[198:201], s[4:5]
	s_waitcnt vmcnt(15)
	v_lshlrev_b32_e32 v129, 16, v202
	v_and_b32_e32 v202, 0xffff0000, v202
	v_mul_f32_e32 v20, v20, v129
	v_mul_f32_e32 v21, v21, v202
	v_lshlrev_b32_e32 v129, 16, v203
	v_and_b32_e32 v203, 0xffff0000, v203
	v_mul_f32_e32 v22, v22, v129
	v_mul_f32_e32 v23, v23, v203
	v_lshlrev_b32_e32 v129, 16, v204
	v_and_b32_e32 v204, 0xffff0000, v204
	v_mul_f32_e32 v16, v16, v129
	v_mul_f32_e32 v17, v17, v204
	v_lshlrev_b32_e32 v129, 16, v205
	v_and_b32_e32 v205, 0xffff0000, v205
	v_mul_f32_e32 v18, v18, v129
	v_mul_f32_e32 v19, v19, v205
	v_cvt_pk_bf16_f32 v202, v20, v21
	v_cvt_pk_bf16_f32 v203, v22, v23
	v_cvt_pk_bf16_f32 v204, v16, v17
	v_cvt_pk_bf16_f32 v205, v18, v19
	global_store_dwordx4 v128, v[202:205], s[4:5] offset:256
	s_add_u32 s4, s0, 0x58000
	s_addc_u32 s5, s1, 0
	s_waitcnt vmcnt(15)
	v_lshlrev_b32_e32 v129, 16, v210
	v_and_b32_e32 v210, 0xffff0000, v210
	v_mul_f32_e32 v12, v12, v129
	v_mul_f32_e32 v13, v13, v210
	v_lshlrev_b32_e32 v129, 16, v211
	v_and_b32_e32 v211, 0xffff0000, v211
	v_mul_f32_e32 v14, v14, v129
	v_mul_f32_e32 v15, v15, v211
	v_lshlrev_b32_e32 v129, 16, v212
	v_and_b32_e32 v212, 0xffff0000, v212
	v_mul_f32_e32 v8, v8, v129
	v_mul_f32_e32 v9, v9, v212
	v_lshlrev_b32_e32 v129, 16, v213
	v_and_b32_e32 v213, 0xffff0000, v213
	v_mul_f32_e32 v10, v10, v129
	v_mul_f32_e32 v11, v11, v213
	v_cvt_pk_bf16_f32 v210, v12, v13
	v_cvt_pk_bf16_f32 v211, v14, v15
	v_cvt_pk_bf16_f32 v212, v8, v9
	v_cvt_pk_bf16_f32 v213, v10, v11
	global_store_dwordx4 v128, v[210:213], s[4:5]
	s_waitcnt vmcnt(15)
	v_lshlrev_b32_e32 v129, 16, v214
	v_and_b32_e32 v214, 0xffff0000, v214
	v_mul_f32_e32 v4, v4, v129
	v_mul_f32_e32 v5, v5, v214
	v_lshlrev_b32_e32 v129, 16, v215
	v_and_b32_e32 v215, 0xffff0000, v215
	v_mul_f32_e32 v6, v6, v129
	v_mul_f32_e32 v7, v7, v215
	v_lshlrev_b32_e32 v129, 16, v216
	v_and_b32_e32 v216, 0xffff0000, v216
	v_mul_f32_e32 v0, v0, v129
	v_mul_f32_e32 v1, v1, v216
	v_lshlrev_b32_e32 v129, 16, v217
	v_and_b32_e32 v217, 0xffff0000, v217
	v_mul_f32_e32 v2, v2, v129
	v_mul_f32_e32 v3, v3, v217
	v_cvt_pk_bf16_f32 v214, v4, v5
	v_cvt_pk_bf16_f32 v215, v6, v7
	v_cvt_pk_bf16_f32 v216, v0, v1
	v_cvt_pk_bf16_f32 v217, v2, v3
	global_store_dwordx4 v128, v[214:217], s[4:5] offset:256
	s_waitcnt vmcnt(0)
	s_barrier
